# plus attention running-max exchange via permlane32 swap instead of ds_bpermute
# speedup vs baseline: 1.0093x; 1.0093x over previous
; __device__ __forceinline__ unsigned cvt_pk_bf16(float lo, float hi) { unsigned r; asm volatile("v_cvt_pk_bf16_f32 %0, %1, %2" : "=v"(r) : "v"(lo), "v"(hi)); return r; }
; template <int NQB> ...
;     ...
;             for (int ks = 0; ks < 4; ++ks) {
;                 const bf16x8 qf = qlds[(qb * 4 + ks) * 64 + lane];
;                 s[0] = __builtin_amdgcn_mfma_f32_32x32x16_bf16(kf[0][ks], qf, s[0], 0, 0, 0);
;                 s[1] = __builtin_amdgcn_mfma_f32_32x32x16_bf16(kf[1][ks], qf, s[1], 0, 0, 0);
;             }
;             __builtin_amdgcn_sched_barrier(0);
;             if (qb == NQB - 1 && t < 8) {
;                 ATTN_KLOAD(t + 1);
;     ...
;             mx = fmaxf(mx, __shfl_xor(mx, 32));
;             const float alpha = __builtin_amdgcn_exp2f(mrun[qb] - mx); mrun[qb] = mx;
;             float ps = 0.f;
; #pragma unroll
;             for (int kb = 0; kb < 2; ++kb)
; #pragma unroll
;                 for (int i = 0; i < 16; ++i) { const float p = __builtin_amdgcn_exp2f(s[kb][i] - mx); s[kb][i] = p; ps += p; }
;             lrun[qb] = lrun[qb] * alpha + ps;
; #pragma unroll
;             for (int db = 0; db < 2; ++db)
; #pragma unroll
;                 for (int i = 0; i < 16; ++i) o[db][qb][i] *= alpha;
; #pragma unroll
;             for (int kb = 0; kb < 2; ++kb)
; #pragma unroll
;                 for (int sx = 0; sx < 2; ++sx) {
;                     u32x4 w; const f32x16& sv = s[kb];
;                     w.x = cvt_pk_bf16(sv[8 * sx + 0], sv[8 * sx + 1]); w.y = cvt_pk_bf16(sv[8 * sx + 2], sv[8 * sx + 3]);
;                     w.z = cvt_pk_bf16(sv[8 * sx + 4], sv[8 * sx + 5]); w.w = cvt_pk_bf16(sv[8 * sx + 6], sv[8 * sx + 7]);
;                     const bf16x8 pf = __builtin_bit_cast(bf16x8, w);
; #pragma unroll
;                     for (int db = 0; db < 2; ++db) o[db][qb] = __builtin_amdgcn_mfma_f32_32x32x16_bf16(vf[kb][sx][db], pf, o[db][qb], 0, 0, 0);
;                 }
;             __builtin_amdgcn_sched_barrier(0);
.LBB0_561:
	s_nop 6
	v_mov_b32_e32 v64, v202
	s_nop 1
	v_permlane32_swap_b32 v64, v202
	v_max_f32_e32 v65, v202, v202
	s_add_i32 s88, s88, 64
	s_waitcnt lgkmcnt(0)
	v_max_f32_e32 v64, v64, v64
	v_max_f32_e32 v222, v65, v64
	v_sub_f32_e32 v65, v164, v222
	v_exp_f32_e32 v223, v65
	v_sub_f32_e32 v65, v165, v222
	v_exp_f32_e32 v165, v65
	v_sub_f32_e32 v65, v166, v222
	v_exp_f32_e32 v224, v65
	v_sub_f32_e32 v65, v167, v222
	v_exp_f32_e32 v225, v65
	v_sub_f32_e32 v65, v168, v222
	v_exp_f32_e32 v226, v65
	v_sub_f32_e32 v65, v169, v222
	v_exp_f32_e32 v227, v65
	v_sub_f32_e32 v65, v170, v222
	v_exp_f32_e32 v228, v65
	v_sub_f32_e32 v65, v171, v222
	v_exp_f32_e32 v229, v65
	v_sub_f32_e32 v65, v172, v222
	v_exp_f32_e32 v230, v65
	v_sub_f32_e32 v65, v173, v222
	v_exp_f32_e32 v231, v65
	v_sub_f32_e32 v65, v174, v222
	v_exp_f32_e32 v232, v65
	v_sub_f32_e32 v65, v175, v222
	v_exp_f32_e32 v233, v65
	v_sub_f32_e32 v65, v176, v222
	v_exp_f32_e32 v234, v65
	v_sub_f32_e32 v65, v177, v222
	v_exp_f32_e32 v235, v65
	v_sub_f32_e32 v65, v178, v222
	v_exp_f32_e32 v236, v65
	v_sub_f32_e32 v65, v179, v222
	v_exp_f32_e32 v237, v65
	v_sub_f32_e32 v65, v180, v222
	v_exp_f32_e32 v238, v65
	v_sub_f32_e32 v65, v181, v222
	v_exp_f32_e32 v239, v65
	v_sub_f32_e32 v65, v182, v222
	v_exp_f32_e32 v241, v65
	v_sub_f32_e32 v65, v183, v222
	v_exp_f32_e32 v242, v65
	v_sub_f32_e32 v65, v184, v222
	v_exp_f32_e32 v244, v65
	v_sub_f32_e32 v65, v185, v222
	v_exp_f32_e32 v246, v65
	v_sub_f32_e32 v65, v186, v222
	v_exp_f32_e32 v248, v65
	v_sub_f32_e32 v65, v187, v222
	v_exp_f32_e32 v250, v65
	v_sub_f32_e32 v65, v194, v222
	v_exp_f32_e32 v251, v65
	v_sub_f32_e32 v65, v195, v222
	v_sub_f32_e32 v64, v188, v222
	v_exp_f32_e32 v252, v65
	v_sub_f32_e32 v65, v196, v222
	v_exp_f32_e32 v253, v65
	v_sub_f32_e32 v65, v197, v222
	v_exp_f32_e32 v164, v64
	v_exp_f32_e32 v243, v65
	v_sub_f32_e32 v65, v198, v222
	v_exp_f32_e32 v245, v65
	v_sub_f32_e32 v65, v199, v222
	v_exp_f32_e32 v247, v65
	v_sub_f32_e32 v65, v200, v222
	v_exp_f32_e32 v249, v65
	v_sub_f32_e32 v65, v201, v222
	v_pk_mul_f32 v[62:63], v[62:63], v[164:165] op_sel_hi:[1,0]
	v_pk_mul_f32 v[60:61], v[60:61], v[164:165] op_sel_hi:[1,0]
	v_pk_mul_f32 v[58:59], v[58:59], v[164:165] op_sel_hi:[1,0]
	v_pk_mul_f32 v[56:57], v[56:57], v[164:165] op_sel_hi:[1,0]
	v_pk_mul_f32 v[54:55], v[54:55], v[164:165] op_sel_hi:[1,0]
	v_pk_mul_f32 v[52:53], v[52:53], v[164:165] op_sel_hi:[1,0]
	v_pk_mul_f32 v[50:51], v[50:51], v[164:165] op_sel_hi:[1,0]
	v_pk_mul_f32 v[48:49], v[48:49], v[164:165] op_sel_hi:[1,0]
	v_pk_mul_f32 v[46:47], v[46:47], v[164:165] op_sel_hi:[1,0]
	v_pk_mul_f32 v[44:45], v[44:45], v[164:165] op_sel_hi:[1,0]
	v_pk_mul_f32 v[42:43], v[42:43], v[164:165] op_sel_hi:[1,0]
	v_pk_mul_f32 v[40:41], v[40:41], v[164:165] op_sel_hi:[1,0]
	v_pk_mul_f32 v[38:39], v[38:39], v[164:165] op_sel_hi:[1,0]
	v_pk_mul_f32 v[36:37], v[36:37], v[164:165] op_sel_hi:[1,0]
	v_pk_mul_f32 v[34:35], v[34:35], v[164:165] op_sel_hi:[1,0]
	v_pk_mul_f32 v[32:33], v[32:33], v[164:165] op_sel_hi:[1,0]
	v_exp_f32_e32 v240, v65
	v_cvt_pk_bf16_f32 v64, v223, v165
	v_cvt_pk_bf16_f32 v65, v224, v225
	v_cvt_pk_bf16_f32 v66, v226, v227
	v_cvt_pk_bf16_f32 v67, v228, v229
	s_waitcnt vmcnt(7)
	v_mfma_f32_32x32x16_bf16 v[48:63], v[156:159], v[64:67], v[48:63]
	s_waitcnt vmcnt(6)
	v_mfma_f32_32x32x16_bf16 v[32:47], v[152:155], v[64:67], v[32:47]
	v_cvt_pk_bf16_f32 v64, v230, v231
	v_cvt_pk_bf16_f32 v65, v232, v233
	v_cvt_pk_bf16_f32 v66, v234, v235
	v_cvt_pk_bf16_f32 v67, v236, v237
	s_waitcnt vmcnt(5)
	v_mfma_f32_32x32x16_bf16 v[48:63], v[148:151], v[64:67], v[48:63]
	s_waitcnt vmcnt(4)
	v_mfma_f32_32x32x16_bf16 v[32:47], v[144:147], v[64:67], v[32:47]
	v_cvt_pk_bf16_f32 v64, v238, v239
	v_cvt_pk_bf16_f32 v65, v241, v242
	v_cvt_pk_bf16_f32 v66, v244, v246
	v_cvt_pk_bf16_f32 v67, v248, v250
	s_waitcnt vmcnt(3)
	v_mfma_f32_32x32x16_bf16 v[48:63], v[140:143], v[64:67], v[48:63]
	s_waitcnt vmcnt(2)
	v_mfma_f32_32x32x16_bf16 v[32:47], v[136:139], v[64:67], v[32:47]
	v_cvt_pk_bf16_f32 v64, v251, v252
	v_cvt_pk_bf16_f32 v65, v253, v243
	v_cvt_pk_bf16_f32 v66, v245, v247
	v_cvt_pk_bf16_f32 v67, v249, v240
	s_waitcnt vmcnt(1)
	v_mfma_f32_32x32x16_bf16 v[48:63], v[132:135], v[64:67], v[48:63]
	s_waitcnt vmcnt(0)
	v_mfma_f32_32x32x16_bf16 v[32:47], v[128:131], v[64:67], v[32:47]
	ds_read_b128 v[64:67], v214 offset:20480
	ds_read_b128 v[166:169], v214 offset:21504
	s_waitcnt lgkmcnt(1)
	v_mfma_f32_32x32x16_bf16 v[80:95], v[124:127], v[64:67], 0
	v_mfma_f32_32x32x16_bf16 v[64:79], v[108:111], v[64:67], 0
	s_waitcnt lgkmcnt(0)
	v_mfma_f32_32x32x16_bf16 v[80:95], v[120:123], v[166:169], v[80:95]
	v_mfma_f32_32x32x16_bf16 v[64:79], v[104:107], v[166:169], v[64:79]
	ds_read_b128 v[166:169], v214 offset:22528
	s_waitcnt lgkmcnt(0)
	v_mfma_f32_32x32x16_bf16 v[80:95], v[116:119], v[166:169], v[80:95]
	v_mfma_f32_32x32x16_bf16 v[64:79], v[100:103], v[166:169], v[64:79]
	ds_read_b128 v[166:169], v214 offset:23552
	s_waitcnt lgkmcnt(0)
	v_mfma_f32_32x32x16_bf16 v[80:95], v[112:115], v[166:169], v[80:95]
	v_mfma_f32_32x32x16_bf16 v[64:79], v[96:99], v[166:169], v[64:79]
	s_andn2_b64 vcc, exec, s[84:85]
	s_cbranch_vccnz .LBB0_563
	s_cmp_lt_i32 s79, 7
	s_cselect_b32 s74, s88, s78
	v_add_u32_e32 v96, s74, v213
	v_lshlrev_b32_e32 v97, 9, v96
	v_lshlrev_b32_e32 v96, 4, v96
	v_and_b32_e32 v98, 0xffffc000, v97
	v_and_b32_e32 v99, 0x1f0, v96
	s_cselect_b32 s95, s3, s81
	s_cselect_b32 s94, s2, s80
	v_add3_u32 v188, v98, v215, v99
	v_lshl_add_u64 v[96:97], v[188:189], 1, s[94:95]
	v_add3_u32 v188, v216, v98, v99
	global_load_dwordx4 v[124:127], v[96:97], off
	global_load_dwordx4 v[120:123], v[96:97], off offset:1024
	global_load_dwordx4 v[116:119], v[96:97], off offset:2048
	global_load_dwordx4 v[112:115], v[96:97], off offset:3072
	v_lshl_add_u64 v[96:97], v[188:189], 1, s[94:95]
	global_load_dwordx4 v[108:111], v[96:97], off
	global_load_dwordx4 v[104:107], v[96:97], off offset:1024
	global_load_dwordx4 v[100:103], v[96:97], off offset:2048
	s_nop 0
	global_load_dwordx4 v[96:99], v[96:97], off offset:3072

; __device__ __forceinline__ unsigned cvt_pk_bf16(float lo, float hi) { unsigned r; asm volatile("v_cvt_pk_bf16_f32 %0, %1, %2" : "=v"(r) : "v"(lo), "v"(hi)); return r; }
; template <int NQB> ...
;     ...
;             mx = fmaxf(mx, __shfl_xor(mx, 32));
;             const float alpha = __builtin_amdgcn_exp2f(mrun[qb] - mx); mrun[qb] = mx;
;             float ps = 0.f;
; #pragma unroll
;             for (int kb = 0; kb < 2; ++kb)
; #pragma unroll
;                 for (int i = 0; i < 16; ++i) { const float p = __builtin_amdgcn_exp2f(s[kb][i] - mx); s[kb][i] = p; ps += p; }
;             lrun[qb] = lrun[qb] * alpha + ps;
; #pragma unroll
;             for (int db = 0; db < 2; ++db)
; #pragma unroll
;                 for (int i = 0; i < 16; ++i) o[db][qb][i] *= alpha;
; #pragma unroll
;             for (int kb = 0; kb < 2; ++kb)
; #pragma unroll
;                 for (int sx = 0; sx < 2; ++sx) {
;                     u32x4 w; const f32x16& sv = s[kb];
;                     w.x = cvt_pk_bf16(sv[8 * sx + 0], sv[8 * sx + 1]); w.y = cvt_pk_bf16(sv[8 * sx + 2], sv[8 * sx + 3]);
;                     w.z = cvt_pk_bf16(sv[8 * sx + 4], sv[8 * sx + 5]); w.w = cvt_pk_bf16(sv[8 * sx + 6], sv[8 * sx + 7]);
;                     const bf16x8 pf = __builtin_bit_cast(bf16x8, w);
; #pragma unroll
;                     for (int db = 0; db < 2; ++db) o[db][qb] = __builtin_amdgcn_mfma_f32_32x32x16_bf16(vf[kb][sx][db], pf, o[db][qb], 0, 0, 0);
;                 }
;             __builtin_amdgcn_sched_barrier(0);
.LBB0_567:
	s_nop 4
	v_add_f32_e32 v64, 0, v223
	v_add_f32_e32 v64, v165, v64
	v_add_f32_e32 v64, v224, v64
	v_add_f32_e32 v64, v225, v64
	v_add_f32_e32 v64, v226, v64
	v_add_f32_e32 v64, v227, v64
	v_add_f32_e32 v64, v228, v64
	v_add_f32_e32 v64, v229, v64
	v_add_f32_e32 v64, v230, v64
	v_add_f32_e32 v64, v231, v64
	v_add_f32_e32 v64, v232, v64
	v_add_f32_e32 v64, v233, v64
	v_add_f32_e32 v64, v234, v64
	v_add_f32_e32 v64, v235, v64
	v_add_f32_e32 v64, v236, v64
	v_add_f32_e32 v64, v237, v64
	v_add_f32_e32 v64, v238, v64
	v_add_f32_e32 v64, v239, v64
	v_add_f32_e32 v64, v241, v64
	v_add_f32_e32 v64, v242, v64
	v_add_f32_e32 v64, v244, v64
	v_add_f32_e32 v64, v246, v64
	v_add_f32_e32 v64, v248, v64
	v_add_f32_e32 v64, v250, v64
	v_add_f32_e32 v64, v251, v64
	v_add_f32_e32 v64, v252, v64
	v_mov_b32_e32 v65, v188
	s_nop 1
	v_permlane32_swap_b32 v65, v188
	v_add_f32_e32 v64, v253, v64
	v_add_f32_e32 v64, v243, v64
	v_add_f32_e32 v64, v245, v64
	v_add_f32_e32 v64, v247, v64
	v_add_f32_e32 v66, v249, v64
	s_waitcnt lgkmcnt(0)
	v_max_f32_e32 v64, v65, v65
	v_max_f32_e32 v65, v188, v188
	v_max_f32_e32 v64, v65, v64
	v_sub_f32_e32 v65, v176, v64
	v_exp_f32_e32 v67, v65
	v_sub_f32_e32 v69, v177, v64
	v_exp_f32_e32 v69, v69
	v_sub_f32_e32 v70, v178, v64
	v_exp_f32_e32 v70, v70
	v_sub_f32_e32 v71, v179, v64
	v_exp_f32_e32 v71, v71
	v_sub_f32_e32 v72, v180, v64
	v_add_f32_e32 v68, 0, v67
	v_exp_f32_e32 v73, v72
	v_sub_f32_e32 v72, v181, v64
	v_add_f32_e32 v68, v69, v68
	v_exp_f32_e32 v74, v72
	v_sub_f32_e32 v72, v182, v64
	v_add_f32_e32 v68, v70, v68
	v_exp_f32_e32 v75, v72
	v_sub_f32_e32 v72, v183, v64
	v_add_f32_e32 v68, v71, v68
	v_exp_f32_e32 v76, v72
	v_sub_f32_e32 v72, v184, v64
	v_add_f32_e32 v68, v73, v68
	v_exp_f32_e32 v77, v72
	v_sub_f32_e32 v72, v185, v64
	v_add_f32_e32 v68, v74, v68
	v_exp_f32_e32 v78, v72
	v_sub_f32_e32 v72, v186, v64
	v_add_f32_e32 v68, v75, v68
	v_exp_f32_e32 v79, v72
	v_sub_f32_e32 v72, v187, v64
	v_add_f32_e32 v68, v76, v68
	v_exp_f32_e32 v80, v72
	v_sub_f32_e32 v72, v194, v64
	v_add_f32_e32 v68, v77, v68
	v_exp_f32_e32 v81, v72
	v_sub_f32_e32 v72, v195, v64
	v_add_f32_e32 v68, v78, v68
	v_exp_f32_e32 v82, v72
	v_sub_f32_e32 v72, v196, v64
	v_add_f32_e32 v68, v79, v68
	v_exp_f32_e32 v83, v72
	v_sub_f32_e32 v72, v197, v64
	v_add_f32_e32 v68, v80, v68
	v_exp_f32_e32 v84, v72
	v_sub_f32_e32 v72, v198, v64
	v_add_f32_e32 v68, v81, v68
	v_exp_f32_e32 v85, v72
	v_sub_f32_e32 v72, v199, v64
	v_add_f32_e32 v68, v82, v68
	v_exp_f32_e32 v86, v72
	v_sub_f32_e32 v72, v200, v64
	v_add_f32_e32 v68, v83, v68
	v_exp_f32_e32 v87, v72
	v_sub_f32_e32 v72, v201, v64
	v_add_f32_e32 v65, v240, v66
	v_sub_f32_e32 v66, v221, v64
	v_add_f32_e32 v68, v84, v68
	v_exp_f32_e32 v88, v72
	v_sub_f32_e32 v72, v202, v64
	v_add_f32_e32 v68, v85, v68
	v_exp_f32_e32 v89, v72
	v_exp_f32_e32 v72, v66
	v_add_f32_e32 v68, v86, v68
	v_add_f32_e32 v68, v87, v68
	v_add_f32_e32 v68, v88, v68
	v_add_f32_e32 v90, v89, v68
	v_sub_f32_e32 v68, v203, v64
	v_sub_f32_e32 v66, v166, v64
	v_pk_mul_f32 v[30:31], v[30:31], v[72:73] op_sel_hi:[1,0]
	v_pk_mul_f32 v[28:29], v[28:29], v[72:73] op_sel_hi:[1,0]
	v_pk_mul_f32 v[26:27], v[26:27], v[72:73] op_sel_hi:[1,0]
	v_pk_mul_f32 v[24:25], v[24:25], v[72:73] op_sel_hi:[1,0]
	v_pk_mul_f32 v[22:23], v[22:23], v[72:73] op_sel_hi:[1,0]
	v_pk_mul_f32 v[20:21], v[20:21], v[72:73] op_sel_hi:[1,0]
	v_pk_mul_f32 v[18:19], v[18:19], v[72:73] op_sel_hi:[1,0]
	v_pk_mul_f32 v[16:17], v[16:17], v[72:73] op_sel_hi:[1,0]
	v_pk_mul_f32 v[14:15], v[14:15], v[72:73] op_sel_hi:[1,0]
	v_pk_mul_f32 v[12:13], v[12:13], v[72:73] op_sel_hi:[1,0]
	v_pk_mul_f32 v[10:11], v[10:11], v[72:73] op_sel_hi:[1,0]
	v_pk_mul_f32 v[8:9], v[8:9], v[72:73] op_sel_hi:[1,0]
	v_pk_mul_f32 v[6:7], v[6:7], v[72:73] op_sel_hi:[1,0]
	v_pk_mul_f32 v[4:5], v[4:5], v[72:73] op_sel_hi:[1,0]
	v_pk_mul_f32 v[2:3], v[2:3], v[72:73] op_sel_hi:[1,0]
	v_pk_mul_f32 v[0:1], v[0:1], v[72:73] op_sel_hi:[1,0]
	v_exp_f32_e32 v91, v68
	v_exp_f32_e32 v92, v66
	v_cvt_pk_bf16_f32 v66, v67, v69
	v_cvt_pk_bf16_f32 v67, v70, v71
	v_cvt_pk_bf16_f32 v68, v73, v74
	v_cvt_pk_bf16_f32 v69, v75, v76
	v_sub_f32_e32 v71, v167, v64
	v_mfma_f32_32x32x16_bf16 v[16:31], v[156:159], v[66:69], v[16:31]
	v_exp_f32_e32 v71, v71
	v_sub_f32_e32 v73, v168, v64
	v_exp_f32_e32 v73, v73
	v_sub_f32_e32 v74, v169, v64
	v_exp_f32_e32 v74, v74
	v_fmac_f32_e32 v65, v220, v164
	v_mfma_f32_32x32x16_bf16 v[0:15], v[152:155], v[66:69], v[0:15]
	v_add_f32_e32 v66, v91, v90
	v_add_f32_e32 v70, v92, v66
	v_cvt_pk_bf16_f32 v66, v77, v78
	v_cvt_pk_bf16_f32 v67, v79, v80
	v_cvt_pk_bf16_f32 v68, v81, v82
	v_cvt_pk_bf16_f32 v69, v83, v84
	v_add_f32_e32 v70, v71, v70
	v_mfma_f32_32x32x16_bf16 v[16:31], v[148:151], v[66:69], v[16:31]
	v_add_f32_e32 v70, v73, v70
	v_add_f32_e32 v75, v74, v70
	v_sub_f32_e32 v70, v171, v64
	v_exp_f32_e32 v77, v70
	v_sub_f32_e32 v70, v172, v64
	v_exp_f32_e32 v78, v70
	v_sub_f32_e32 v70, v173, v64
	v_mfma_f32_32x32x16_bf16 v[0:15], v[144:147], v[66:69], v[0:15]
	v_sub_f32_e32 v66, v170, v64
	v_exp_f32_e32 v76, v66
	v_cvt_pk_bf16_f32 v66, v85, v86
	v_cvt_pk_bf16_f32 v67, v87, v88
	v_cvt_pk_bf16_f32 v68, v89, v91
	v_cvt_pk_bf16_f32 v69, v92, v71
	v_exp_f32_e32 v79, v70
	v_mfma_f32_32x32x16_bf16 v[16:31], v[140:143], v[66:69], v[16:31]
	v_sub_f32_e32 v70, v174, v64
	v_mfma_f32_32x32x16_bf16 v[0:15], v[136:139], v[66:69], v[0:15]
	v_sub_f32_e32 v67, v175, v64
	v_exp_f32_e32 v66, v70
	v_exp_f32_e32 v67, v67
	v_cvt_pk_bf16_f32 v68, v73, v74
	v_cvt_pk_bf16_f32 v69, v76, v77
	v_cvt_pk_bf16_f32 v70, v78, v79
	v_cvt_pk_bf16_f32 v71, v66, v67
	v_add_f32_e32 v73, v76, v75
	v_mfma_f32_32x32x16_bf16 v[16:31], v[132:135], v[68:71], v[16:31]
	v_add_f32_e32 v73, v77, v73
	v_add_f32_e32 v73, v78, v73
	v_add_f32_e32 v73, v79, v73
	v_add_f32_e32 v66, v66, v73
	v_add_f32_e32 v66, v67, v66
	v_fmac_f32_e32 v66, v219, v72
	v_mfma_f32_32x32x16_bf16 v[0:15], v[128:131], v[68:71], v[0:15]
	s_add_i32 s74, s79, 1
	s_cmp_gt_i32 s79, 7
	v_add_u32_e32 v218, 0xffffff00, v218
	s_cbranch_scc1 .LBB0_569
	v_mov_b32_e32 v220, v65
	v_mov_b32_e32 v219, v66
	v_mov_b32_e32 v188, v222
	v_mov_b32_e32 v221, v64
	s_mov_b32 s79, s74
	s_branch .LBB0_557
